# xattn: K image row stride 544 (conflict-free K fragment reads) and one static s_setprio 1 for waves 4-7
# speedup vs baseline: 1.0047x; 1.0047x over previous
.LBB0_1947:
	v_readlane_b32 s4, v244, 47
	s_cmp_lt_i32 s4, 10
	s_cselect_b64 s[2:3], -1, 0
	s_and_b64 s[2:3], s[2:3], s[0:1]
	s_cmpk_lt_i32 s69, 0x600
	s_cselect_b64 s[0:1], -1, 0
	s_and_b64 s[0:1], s[2:3], s[0:1]
	s_andn2_b64 vcc, exec, s[0:1]
	v_readlane_b32 s5, v244, 48
	v_readlane_b32 s6, v244, 49
	v_readlane_b32 s7, v244, 50
	s_cbranch_vccnz .LBB0_1956
	v_and_b32_e32 v249, 63, v182
	v_readlane_b32 s4, v244, 6
	v_readlane_b32 s5, v244, 7
	v_readlane_b32 s6, v244, 39
	v_readlane_b32 s7, v244, 40
	v_readlane_b32 s8, v244, 41
	v_readlane_b32 s9, v244, 42
	v_lshlrev_b32_e32 v242, 2, v249
	s_nop 3
	global_load_dword v216, v242, s[6:7] offset:0
	global_load_dword v217, v242, s[6:7] offset:256
	global_load_dword v218, v242, s[6:7] offset:512
	global_load_dword v219, v242, s[6:7] offset:768
	global_load_dword v220, v242, s[8:9] offset:0
	global_load_dword v221, v242, s[8:9] offset:256
	global_load_dword v222, v242, s[8:9] offset:512
	global_load_dword v223, v242, s[8:9] offset:768
	v_and_b32_e32 v243, 15, v182
	v_bfe_u32 v245, v182, 4, 2
	v_lshl_or_b32 v246, s88, 4, v243
	v_lshlrev_b32_e32 v228, 11, v246
	v_lshl_add_u32 v238, v245, 3, v228
	v_lshl_add_u32 v228, v245, 4, v228
	v_add_u32_e32 v229, 0x40000, v228
	v_add_u32_e32 v239, 0x40000, v238
	v_lshlrev_b32_e32 v230, 4, v246
	v_mul_u32_u24_e32 v231, 528, v243
	v_lshl_add_u32 v232, v245, 3, v231
	v_mul_u32_u24_e32 v231, 544, v243
	v_lshl_add_u32 v231, v245, 4, v231
	v_lshrrev_b32_e32 v243, 5, v182
	v_and_b32_e32 v245, 31, v182
	v_lshlrev_b32_e32 v245, 4, v245
	v_lshl_add_u32 v224, v243, 11, v245
	v_mul_u32_u24_e32 v225, 5120, v243
	v_add_u32_e32 v225, v225, v245
	v_mul_u32_u24_e32 v226, 544, v243
	v_add_u32_e32 v226, v226, v245
	v_add_u32_e32 v227, 69632, v226
	v_and_b32_e32 v250, 3, v243
	v_bfe_u32 v242, v243, 2, 1
	v_lshl_or_b32 v250, v242, 4, v250
	v_bfe_u32 v242, v243, 3, 1
	v_lshl_or_b32 v250, v242, 2, v250
	v_mul_u32_u24_e32 v250, 528, v250
	v_add_u32_e32 v250, v250, v245
	v_add_u32_e32 v251, 67584, v250
	v_xor_b32_e32 v236, 16, v249
	v_lshlrev_b32_e32 v236, 2, v236
	v_xor_b32_e32 v237, 32, v249
	v_lshlrev_b32_e32 v237, 2, v237
	v_mov_b32_e32 v181, 0x358637bd
	s_waitcnt vmcnt(0)
	v_mul_f32_e32 v216, v216, v220
	v_mul_f32_e32 v217, v217, v221
	v_mul_f32_e32 v218, v218, v222
	v_mul_f32_e32 v219, v219, v223
	v_max_f32_e64 v216, |v216|, |v217|
	v_max_f32_e64 v218, |v218|, |v219|
	v_max_f32_e32 v216, v216, v218
	v_xor_b32_e32 v242, 1, v249
	v_lshlrev_b32_e32 v242, 2, v242
	ds_bpermute_b32 v243, v242, v216
	s_waitcnt lgkmcnt(0)
	v_max_f32_e32 v216, v216, v243
	v_xor_b32_e32 v242, 2, v249
	v_lshlrev_b32_e32 v242, 2, v242
	ds_bpermute_b32 v243, v242, v216
	s_waitcnt lgkmcnt(0)
	v_max_f32_e32 v216, v216, v243
	v_xor_b32_e32 v242, 4, v249
	v_lshlrev_b32_e32 v242, 2, v242
	ds_bpermute_b32 v243, v242, v216
	s_waitcnt lgkmcnt(0)
	v_max_f32_e32 v216, v216, v243
	v_xor_b32_e32 v242, 8, v249
	v_lshlrev_b32_e32 v242, 2, v242
	ds_bpermute_b32 v243, v242, v216
	s_waitcnt lgkmcnt(0)
	v_max_f32_e32 v216, v216, v243
	v_xor_b32_e32 v242, 16, v249
	v_lshlrev_b32_e32 v242, 2, v242
	ds_bpermute_b32 v243, v242, v216
	s_waitcnt lgkmcnt(0)
	v_max_f32_e32 v216, v216, v243
	v_xor_b32_e32 v242, 32, v249
	v_lshlrev_b32_e32 v242, 2, v242
	ds_bpermute_b32 v243, v242, v216
	s_waitcnt lgkmcnt(0)
	v_max_f32_e32 v216, v216, v243
	v_mul_f32_e32 v180, 0x41b8aa3b, v216
	s_and_b32 s0, s69, 31
	s_lshr_b32 s1, s69, 8
	s_lshl_b32 s1, s1, 5
	s_add_i32 s1, s1, s0
	s_mul_i32 s0, s1, 2731
	s_lshr_b32 s0, s0, 16
	s_mul_i32 s17, s0, 24
	s_sub_i32 s1, s1, s17
	s_bfe_u32 s17, s69, 0x30005
	s_mul_i32 s17, s17, 24
	s_add_i32 s1, s1, s17
	s_lshl_b32 s11, s1, 19
	s_lshl_b32 s12, s0, 9
	s_add_u32 s11, s11, s12
	s_add_u32 s12, s11, 0xf000000
	s_add_u32 s10, s4, s12
	s_addc_u32 s11, s5, 0
	s_lshl_b32 s12, s1, 12
	s_lshl_b32 s13, s0, 2
	s_add_u32 s12, s12, s13
	s_add_u32 s12, s12, 0x1fa60000
	s_add_u32 s12, s4, s12
	s_addc_u32 s13, s5, 0
	global_load_dwordx4 v[0:3], v228, s[10:11] offset:0
	global_load_dwordx4 v[4:7], v228, s[10:11] offset:64
	global_load_dwordx4 v[8:11], v228, s[10:11] offset:128
	global_load_dwordx4 v[12:15], v228, s[10:11] offset:192
	global_load_dwordx4 v[16:19], v228, s[10:11] offset:256
	global_load_dwordx4 v[20:23], v228, s[10:11] offset:320
	global_load_dwordx4 v[24:27], v228, s[10:11] offset:384
	global_load_dwordx4 v[28:31], v228, s[10:11] offset:448
	global_load_dwordx4 v[32:35], v229, s[10:11] offset:0
	global_load_dwordx4 v[36:39], v229, s[10:11] offset:64
	global_load_dwordx4 v[40:43], v229, s[10:11] offset:128
	global_load_dwordx4 v[44:47], v229, s[10:11] offset:192
	global_load_dwordx4 v[48:51], v229, s[10:11] offset:256
	global_load_dwordx4 v[52:55], v229, s[10:11] offset:320
	global_load_dwordx4 v[56:59], v229, s[10:11] offset:384
	global_load_dwordx4 v[60:63], v229, s[10:11] offset:448
	global_load_dword v247, v230, s[12:13]
	global_load_dword v248, v230, s[12:13] offset:2048
	s_lshr_b32 s10, s1, 5
	s_sub_i32 s11, s1, 64
	s_lshr_b32 s11, s11, 4
	s_add_i32 s11, s11, 2
	s_cmp_lt_u32 s1, 64
	s_cselect_b32 s10, s10, s11
	s_lshl_b32 s11, s10, 19
	s_lshl_b32 s12, s0, 9
	s_add_u32 s11, s11, s12
	s_add_u32 s11, s11, 0x15040000
	s_add_u32 s6, s4, s11
	s_addc_u32 s7, s5, 0
	global_load_dwordx4 v[184:187], v224, s[6:7]
	s_add_u32 s6, s6, 0x8000
	s_addc_u32 s7, s7, 0
	global_load_dwordx4 v[188:191], v224, s[6:7]
	s_add_u32 s6, s6, 0x8000
	s_addc_u32 s7, s7, 0
	global_load_dwordx4 v[192:195], v224, s[6:7]
	s_add_u32 s6, s6, 0x8000
	s_addc_u32 s7, s7, 0
	global_load_dwordx4 v[196:199], v224, s[6:7]
	s_add_u32 s6, s6, 0x8000
	s_addc_u32 s7, s7, 0
	global_load_dwordx4 v[200:203], v224, s[6:7]
	s_add_u32 s6, s6, 0x8000
	s_addc_u32 s7, s7, 0
	global_load_dwordx4 v[204:207], v224, s[6:7]
	s_add_u32 s6, s6, 0x8000
	s_addc_u32 s7, s7, 0
	global_load_dwordx4 v[208:211], v224, s[6:7]
	s_add_u32 s6, s6, 0x8000
	s_addc_u32 s7, s7, 0
	global_load_dwordx4 v[212:215], v224, s[6:7]
	s_cmp_ge_u32 s88, 4
	s_cbranch_scc0 .Lxa_noprio
	s_setprio 1
.Lxa_noprio:
.Lxa_unit:
	s_and_b32 s0, s69, 31
	s_lshr_b32 s1, s69, 8
	s_lshl_b32 s1, s1, 5
	s_add_i32 s1, s1, s0
	s_mul_i32 s0, s1, 2731
	s_lshr_b32 s0, s0, 16
	s_mul_i32 s17, s0, 24
	s_sub_i32 s1, s1, s17
	s_bfe_u32 s17, s69, 0x30005
	s_mul_i32 s17, s17, 24
	s_add_i32 s1, s1, s17
	s_lshr_b32 s10, s1, 5
	s_sub_i32 s11, s1, 64
	s_lshr_b32 s11, s11, 4
	s_add_i32 s11, s11, 2
	s_cmp_lt_u32 s1, 64
	s_cselect_b32 s10, s10, s11
	s_lshl_b32 s11, s10, 19
	s_lshl_b32 s12, s0, 9
	s_add_u32 s11, s11, s12
	s_add_u32 s11, s11, 0x15000000
	s_add_u32 s6, s4, s11
	s_addc_u32 s7, s5, 0
	s_mul_i32 s11, s0, 0x140000
	s_lshl_b32 s12, s10, 9
	s_add_u32 s11, s11, s12
	s_add_u32 s11, s11, 0x15800000
	s_add_u32 s8, s4, s11
	s_addc_u32 s9, s5, 0
	s_lshl_b32 s12, s1, 19
	s_lshl_b32 s13, s0, 9
	s_add_u32 s12, s12, s13
	s_add_u32 s12, s12, 0x9000000
	s_add_u32 s14, s4, s12
	s_addc_u32 s15, s5, 0
	global_load_dwordx4 v[128:131], v224, s[6:7]
	s_add_u32 s6, s6, 0x8000
	s_addc_u32 s7, s7, 0
	global_load_dwordx4 v[132:135], v224, s[6:7]
	s_add_u32 s6, s6, 0x8000
	s_addc_u32 s7, s7, 0
	global_load_dwordx4 v[136:139], v224, s[6:7]
	s_add_u32 s6, s6, 0x8000
	s_addc_u32 s7, s7, 0
	global_load_dwordx4 v[140:143], v224, s[6:7]
	s_add_u32 s6, s6, 0x8000
	s_addc_u32 s7, s7, 0
	global_load_dwordx4 v[144:147], v224, s[6:7]
	s_add_u32 s6, s6, 0x8000
	s_addc_u32 s7, s7, 0
	global_load_dwordx4 v[148:151], v224, s[6:7]
	s_add_u32 s6, s6, 0x8000
	s_addc_u32 s7, s7, 0
	global_load_dwordx4 v[152:155], v224, s[6:7]
	s_add_u32 s6, s6, 0x8000
	s_addc_u32 s7, s7, 0
	global_load_dwordx4 v[156:159], v224, s[6:7]
	s_add_u32 s6, s6, 0x8000
	s_addc_u32 s7, s7, 0
	s_waitcnt vmcnt(4)
	ds_write_b128 v226, v[128:131] offset:0
	ds_write_b128 v226, v[132:135] offset:8704
	ds_write_b128 v226, v[136:139] offset:17408
	ds_write_b128 v226, v[140:143] offset:26112
	s_waitcnt vmcnt(0)
	ds_write_b128 v226, v[144:147] offset:34816
	ds_write_b128 v226, v[148:151] offset:43520
	ds_write_b128 v226, v[152:155] offset:52224
	ds_write_b128 v226, v[156:159] offset:60928
	ds_write_b128 v227, v[184:187] offset:0
	ds_write_b128 v227, v[188:191] offset:8704
	ds_write_b128 v227, v[192:195] offset:17408
	ds_write_b128 v227, v[196:199] offset:26112
	ds_write_b128 v227, v[200:203] offset:34816
	ds_write_b128 v227, v[204:207] offset:43520
	ds_write_b128 v227, v[208:211] offset:52224
	ds_write_b128 v227, v[212:215] offset:60928
	s_waitcnt vmcnt(0)
	v_fmamk_f32 v178, v247, 0x3b800000, v181
	v_fmamk_f32 v179, v248, 0x3b800000, v181
	v_rsq_f32_e32 v178, v178
	v_rsq_f32_e32 v179, v179
	v_mov_b32_e32 v176, 0
	v_mov_b32_e32 v177, 0
	v_mul_f32_e32 v178, 0x3db8aa3b, v178
	v_mul_f32_e32 v179, 0x3db8aa3b, v179
	s_waitcnt lgkmcnt(0)
	s_barrier
	v_mov_b32_e32 v233, v231
	ds_read_b128 v[128:131], v233 offset:0
	ds_read_b128 v[132:135], v233 offset:64
	ds_read_b128 v[136:139], v233 offset:128
	ds_read_b128 v[140:143], v233 offset:192
	ds_read_b128 v[144:147], v233 offset:256
	ds_read_b128 v[148:151], v233 offset:320
	ds_read_b128 v[152:155], v233 offset:384
	ds_read_b128 v[156:159], v233 offset:448
	s_waitcnt lgkmcnt(0)
	ds_read_b128 v[184:187], v233 offset:8704
	ds_read_b128 v[188:191], v233 offset:8768
	ds_read_b128 v[192:195], v233 offset:8832
	ds_read_b128 v[196:199], v233 offset:8896
	ds_read_b128 v[200:203], v233 offset:8960
	ds_read_b128 v[204:207], v233 offset:9024
	ds_read_b128 v[208:211], v233 offset:9088
	ds_read_b128 v[212:215], v233 offset:9152
	v_mfma_f32_16x16x32_bf16 v[160:163], v[128:131], v[0:3], 0
	v_mfma_f32_16x16x32_bf16 v[164:167], v[128:131], v[32:35], 0
	v_mfma_f32_16x16x32_bf16 v[160:163], v[132:135], v[4:7], v[160:163]
	v_mfma_f32_16x16x32_bf16 v[164:167], v[132:135], v[36:39], v[164:167]
	v_mfma_f32_16x16x32_bf16 v[160:163], v[136:139], v[8:11], v[160:163]
	v_mfma_f32_16x16x32_bf16 v[164:167], v[136:139], v[40:43], v[164:167]
	v_mfma_f32_16x16x32_bf16 v[160:163], v[140:143], v[12:15], v[160:163]
	v_mfma_f32_16x16x32_bf16 v[164:167], v[140:143], v[44:47], v[164:167]
	v_mfma_f32_16x16x32_bf16 v[160:163], v[144:147], v[16:19], v[160:163]
	v_mfma_f32_16x16x32_bf16 v[164:167], v[144:147], v[48:51], v[164:167]
	v_mfma_f32_16x16x32_bf16 v[160:163], v[148:151], v[20:23], v[160:163]
	v_mfma_f32_16x16x32_bf16 v[164:167], v[148:151], v[52:55], v[164:167]
	v_mfma_f32_16x16x32_bf16 v[160:163], v[152:155], v[24:27], v[160:163]
	v_mfma_f32_16x16x32_bf16 v[164:167], v[152:155], v[56:59], v[164:167]
	v_mfma_f32_16x16x32_bf16 v[160:163], v[156:159], v[28:31], v[160:163]
	v_mfma_f32_16x16x32_bf16 v[164:167], v[156:159], v[60:63], v[164:167]
	s_waitcnt lgkmcnt(0)
	ds_read_b128 v[128:131], v233 offset:17408
	ds_read_b128 v[132:135], v233 offset:17472
	ds_read_b128 v[136:139], v233 offset:17536
	ds_read_b128 v[140:143], v233 offset:17600
	ds_read_b128 v[144:147], v233 offset:17664
	ds_read_b128 v[148:151], v233 offset:17728
	ds_read_b128 v[152:155], v233 offset:17792
	ds_read_b128 v[156:159], v233 offset:17856
	v_mfma_f32_16x16x32_bf16 v[168:171], v[184:187], v[0:3], 0
	v_fma_f32 v216, v160, v178, -v180
	v_fma_f32 v217, v161, v178, -v180
	v_mfma_f32_16x16x32_bf16 v[172:175], v[184:187], v[32:35], 0
	v_fma_f32 v218, v162, v178, -v180
	v_fma_f32 v219, v163, v178, -v180
	v_mfma_f32_16x16x32_bf16 v[168:171], v[188:191], v[4:7], v[168:171]
	v_exp_f32_e32 v216, v216
	v_exp_f32_e32 v217, v217
	v_mfma_f32_16x16x32_bf16 v[172:175], v[188:191], v[36:39], v[172:175]
	v_exp_f32_e32 v218, v218
	v_exp_f32_e32 v219, v219
	v_mfma_f32_16x16x32_bf16 v[168:171], v[192:195], v[8:11], v[168:171]
	v_fma_f32 v220, v164, v179, -v180
	v_fma_f32 v221, v165, v179, -v180
	v_mfma_f32_16x16x32_bf16 v[172:175], v[192:195], v[40:43], v[172:175]
	v_fma_f32 v222, v166, v179, -v180
	v_fma_f32 v223, v167, v179, -v180
	v_mfma_f32_16x16x32_bf16 v[168:171], v[196:199], v[12:15], v[168:171]
	v_exp_f32_e32 v220, v220
	v_exp_f32_e32 v221, v221
	v_mfma_f32_16x16x32_bf16 v[172:175], v[196:199], v[44:47], v[172:175]
	v_exp_f32_e32 v222, v222
	v_exp_f32_e32 v223, v223
	v_mfma_f32_16x16x32_bf16 v[168:171], v[200:203], v[16:19], v[168:171]
	v_add_f32_e32 v176, v176, v216
	v_add_f32_e32 v176, v176, v217
	v_mfma_f32_16x16x32_bf16 v[172:175], v[200:203], v[48:51], v[172:175]
	v_cvt_pk_bf16_f32 v64, v216, v217
	v_add_f32_e32 v176, v176, v218
	v_mfma_f32_16x16x32_bf16 v[168:171], v[204:207], v[20:23], v[168:171]
	v_add_f32_e32 v176, v176, v219
	v_cvt_pk_bf16_f32 v65, v218, v219
	v_mfma_f32_16x16x32_bf16 v[172:175], v[204:207], v[52:55], v[172:175]
	v_add_f32_e32 v177, v177, v220
	v_add_f32_e32 v177, v177, v221
	v_mfma_f32_16x16x32_bf16 v[168:171], v[208:211], v[24:27], v[168:171]
	v_cvt_pk_bf16_f32 v96, v220, v221
	v_add_f32_e32 v177, v177, v222
	v_mfma_f32_16x16x32_bf16 v[172:175], v[208:211], v[56:59], v[172:175]
	v_add_f32_e32 v177, v177, v223
	v_cvt_pk_bf16_f32 v97, v222, v223
	v_mfma_f32_16x16x32_bf16 v[168:171], v[212:215], v[28:31], v[168:171]
	v_mfma_f32_16x16x32_bf16 v[172:175], v[212:215], v[60:63], v[172:175]
	s_waitcnt lgkmcnt(0)
	ds_read_b128 v[184:187], v233 offset:26112
	ds_read_b128 v[188:191], v233 offset:26176
	ds_read_b128 v[192:195], v233 offset:26240
	ds_read_b128 v[196:199], v233 offset:26304
	ds_read_b128 v[200:203], v233 offset:26368
	ds_read_b128 v[204:207], v233 offset:26432
	ds_read_b128 v[208:211], v233 offset:26496
	ds_read_b128 v[212:215], v233 offset:26560
	v_mfma_f32_16x16x32_bf16 v[160:163], v[128:131], v[0:3], 0
	v_fma_f32 v216, v168, v178, -v180
	v_fma_f32 v217, v169, v178, -v180
	v_mfma_f32_16x16x32_bf16 v[164:167], v[128:131], v[32:35], 0
	v_fma_f32 v218, v170, v178, -v180
	v_fma_f32 v219, v171, v178, -v180
	v_mfma_f32_16x16x32_bf16 v[160:163], v[132:135], v[4:7], v[160:163]
	v_exp_f32_e32 v216, v216
	v_exp_f32_e32 v217, v217
	v_mfma_f32_16x16x32_bf16 v[164:167], v[132:135], v[36:39], v[164:167]
	v_exp_f32_e32 v218, v218
	v_exp_f32_e32 v219, v219
	v_mfma_f32_16x16x32_bf16 v[160:163], v[136:139], v[8:11], v[160:163]
	v_fma_f32 v220, v172, v179, -v180
	v_fma_f32 v221, v173, v179, -v180
	v_mfma_f32_16x16x32_bf16 v[164:167], v[136:139], v[40:43], v[164:167]
	v_fma_f32 v222, v174, v179, -v180
	v_fma_f32 v223, v175, v179, -v180
	v_mfma_f32_16x16x32_bf16 v[160:163], v[140:143], v[12:15], v[160:163]
	v_exp_f32_e32 v220, v220
	v_exp_f32_e32 v221, v221
	v_mfma_f32_16x16x32_bf16 v[164:167], v[140:143], v[44:47], v[164:167]
	v_exp_f32_e32 v222, v222
	v_exp_f32_e32 v223, v223
	v_mfma_f32_16x16x32_bf16 v[160:163], v[144:147], v[16:19], v[160:163]
	v_add_f32_e32 v176, v176, v216
	v_add_f32_e32 v176, v176, v217
	v_mfma_f32_16x16x32_bf16 v[164:167], v[144:147], v[48:51], v[164:167]
	v_cvt_pk_bf16_f32 v66, v216, v217
	v_add_f32_e32 v176, v176, v218
	v_mfma_f32_16x16x32_bf16 v[160:163], v[148:151], v[20:23], v[160:163]
	v_add_f32_e32 v176, v176, v219
	v_cvt_pk_bf16_f32 v67, v218, v219
	v_mfma_f32_16x16x32_bf16 v[164:167], v[148:151], v[52:55], v[164:167]
	v_add_f32_e32 v177, v177, v220
	v_add_f32_e32 v177, v177, v221
	v_mfma_f32_16x16x32_bf16 v[160:163], v[152:155], v[24:27], v[160:163]
	v_cvt_pk_bf16_f32 v98, v220, v221
	v_add_f32_e32 v177, v177, v222
	v_mfma_f32_16x16x32_bf16 v[164:167], v[152:155], v[56:59], v[164:167]
	v_add_f32_e32 v177, v177, v223
	v_cvt_pk_bf16_f32 v99, v222, v223
	v_mfma_f32_16x16x32_bf16 v[160:163], v[156:159], v[28:31], v[160:163]
	v_mfma_f32_16x16x32_bf16 v[164:167], v[156:159], v[60:63], v[164:167]
	s_waitcnt lgkmcnt(0)
	ds_read_b128 v[128:131], v233 offset:34816
	ds_read_b128 v[132:135], v233 offset:34880
	ds_read_b128 v[136:139], v233 offset:34944
	ds_read_b128 v[140:143], v233 offset:35008
	ds_read_b128 v[144:147], v233 offset:35072
	ds_read_b128 v[148:151], v233 offset:35136
	ds_read_b128 v[152:155], v233 offset:35200
	ds_read_b128 v[156:159], v233 offset:35264
	v_mfma_f32_16x16x32_bf16 v[168:171], v[184:187], v[0:3], 0
	v_fma_f32 v216, v160, v178, -v180
	v_fma_f32 v217, v161, v178, -v180
	v_mfma_f32_16x16x32_bf16 v[172:175], v[184:187], v[32:35], 0
	v_fma_f32 v218, v162, v178, -v180
	v_fma_f32 v219, v163, v178, -v180
	v_mfma_f32_16x16x32_bf16 v[168:171], v[188:191], v[4:7], v[168:171]
	v_exp_f32_e32 v216, v216
	v_exp_f32_e32 v217, v217
	v_mfma_f32_16x16x32_bf16 v[172:175], v[188:191], v[36:39], v[172:175]
	v_exp_f32_e32 v218, v218
	v_exp_f32_e32 v219, v219
	v_mfma_f32_16x16x32_bf16 v[168:171], v[192:195], v[8:11], v[168:171]
	v_fma_f32 v220, v164, v179, -v180
	v_fma_f32 v221, v165, v179, -v180
	v_mfma_f32_16x16x32_bf16 v[172:175], v[192:195], v[40:43], v[172:175]
	v_fma_f32 v222, v166, v179, -v180
	v_fma_f32 v223, v167, v179, -v180
	v_mfma_f32_16x16x32_bf16 v[168:171], v[196:199], v[12:15], v[168:171]
	v_exp_f32_e32 v220, v220
	v_exp_f32_e32 v221, v221
	v_mfma_f32_16x16x32_bf16 v[172:175], v[196:199], v[44:47], v[172:175]
	v_exp_f32_e32 v222, v222
	v_exp_f32_e32 v223, v223
	v_mfma_f32_16x16x32_bf16 v[168:171], v[200:203], v[16:19], v[168:171]
	v_add_f32_e32 v176, v176, v216
	v_add_f32_e32 v176, v176, v217
	v_mfma_f32_16x16x32_bf16 v[172:175], v[200:203], v[48:51], v[172:175]
	v_cvt_pk_bf16_f32 v68, v216, v217
	v_add_f32_e32 v176, v176, v218
	v_mfma_f32_16x16x32_bf16 v[168:171], v[204:207], v[20:23], v[168:171]
	v_add_f32_e32 v176, v176, v219
	v_cvt_pk_bf16_f32 v69, v218, v219
	v_mfma_f32_16x16x32_bf16 v[172:175], v[204:207], v[52:55], v[172:175]
	v_add_f32_e32 v177, v177, v220
	v_add_f32_e32 v177, v177, v221
	v_mfma_f32_16x16x32_bf16 v[168:171], v[208:211], v[24:27], v[168:171]
	v_cvt_pk_bf16_f32 v100, v220, v221
	v_add_f32_e32 v177, v177, v222
	v_mfma_f32_16x16x32_bf16 v[172:175], v[208:211], v[56:59], v[172:175]
	v_add_f32_e32 v177, v177, v223
	v_cvt_pk_bf16_f32 v101, v222, v223
	v_mfma_f32_16x16x32_bf16 v[168:171], v[212:215], v[28:31], v[168:171]
	v_mfma_f32_16x16x32_bf16 v[172:175], v[212:215], v[60:63], v[172:175]
	s_waitcnt lgkmcnt(0)
	ds_read_b128 v[184:187], v233 offset:43520
	ds_read_b128 v[188:191], v233 offset:43584
	ds_read_b128 v[192:195], v233 offset:43648
	ds_read_b128 v[196:199], v233 offset:43712
	ds_read_b128 v[200:203], v233 offset:43776
	ds_read_b128 v[204:207], v233 offset:43840
	ds_read_b128 v[208:211], v233 offset:43904
	ds_read_b128 v[212:215], v233 offset:43968
	v_mfma_f32_16x16x32_bf16 v[160:163], v[128:131], v[0:3], 0
	v_fma_f32 v216, v168, v178, -v180
	v_fma_f32 v217, v169, v178, -v180
	v_mfma_f32_16x16x32_bf16 v[164:167], v[128:131], v[32:35], 0
	v_fma_f32 v218, v170, v178, -v180
	v_fma_f32 v219, v171, v178, -v180
	v_mfma_f32_16x16x32_bf16 v[160:163], v[132:135], v[4:7], v[160:163]
	v_exp_f32_e32 v216, v216
	v_exp_f32_e32 v217, v217
	v_mfma_f32_16x16x32_bf16 v[164:167], v[132:135], v[36:39], v[164:167]
	v_exp_f32_e32 v218, v218
	v_exp_f32_e32 v219, v219
	v_mfma_f32_16x16x32_bf16 v[160:163], v[136:139], v[8:11], v[160:163]
	v_fma_f32 v220, v172, v179, -v180
	v_fma_f32 v221, v173, v179, -v180
	v_mfma_f32_16x16x32_bf16 v[164:167], v[136:139], v[40:43], v[164:167]
	v_fma_f32 v222, v174, v179, -v180
	v_fma_f32 v223, v175, v179, -v180
	v_mfma_f32_16x16x32_bf16 v[160:163], v[140:143], v[12:15], v[160:163]
	v_exp_f32_e32 v220, v220
	v_exp_f32_e32 v221, v221
	v_mfma_f32_16x16x32_bf16 v[164:167], v[140:143], v[44:47], v[164:167]
	v_exp_f32_e32 v222, v222
	v_exp_f32_e32 v223, v223
	v_mfma_f32_16x16x32_bf16 v[160:163], v[144:147], v[16:19], v[160:163]
	v_add_f32_e32 v176, v176, v216
	v_add_f32_e32 v176, v176, v217
	v_mfma_f32_16x16x32_bf16 v[164:167], v[144:147], v[48:51], v[164:167]
	v_cvt_pk_bf16_f32 v70, v216, v217
	v_add_f32_e32 v176, v176, v218
	v_mfma_f32_16x16x32_bf16 v[160:163], v[148:151], v[20:23], v[160:163]
	v_add_f32_e32 v176, v176, v219
	v_cvt_pk_bf16_f32 v71, v218, v219
	v_mfma_f32_16x16x32_bf16 v[164:167], v[148:151], v[52:55], v[164:167]
	v_add_f32_e32 v177, v177, v220
	v_add_f32_e32 v177, v177, v221
	v_mfma_f32_16x16x32_bf16 v[160:163], v[152:155], v[24:27], v[160:163]
	v_cvt_pk_bf16_f32 v102, v220, v221
	v_add_f32_e32 v177, v177, v222
	v_mfma_f32_16x16x32_bf16 v[164:167], v[152:155], v[56:59], v[164:167]
	v_add_f32_e32 v177, v177, v223
	v_cvt_pk_bf16_f32 v103, v222, v223
	v_mfma_f32_16x16x32_bf16 v[160:163], v[156:159], v[28:31], v[160:163]
	v_mfma_f32_16x16x32_bf16 v[164:167], v[156:159], v[60:63], v[164:167]
	s_waitcnt lgkmcnt(0)
	ds_read_b128 v[128:131], v233 offset:52224
	ds_read_b128 v[132:135], v233 offset:52288
	ds_read_b128 v[136:139], v233 offset:52352
	ds_read_b128 v[140:143], v233 offset:52416
	ds_read_b128 v[144:147], v233 offset:52480
	ds_read_b128 v[148:151], v233 offset:52544
	ds_read_b128 v[152:155], v233 offset:52608
	ds_read_b128 v[156:159], v233 offset:52672
	v_mfma_f32_16x16x32_bf16 v[168:171], v[184:187], v[0:3], 0
	v_fma_f32 v216, v160, v178, -v180
	v_fma_f32 v217, v161, v178, -v180
	v_mfma_f32_16x16x32_bf16 v[172:175], v[184:187], v[32:35], 0
	v_fma_f32 v218, v162, v178, -v180
	v_fma_f32 v219, v163, v178, -v180
	v_mfma_f32_16x16x32_bf16 v[168:171], v[188:191], v[4:7], v[168:171]
	v_exp_f32_e32 v216, v216
	v_exp_f32_e32 v217, v217
	v_mfma_f32_16x16x32_bf16 v[172:175], v[188:191], v[36:39], v[172:175]
	v_exp_f32_e32 v218, v218
	v_exp_f32_e32 v219, v219
	v_mfma_f32_16x16x32_bf16 v[168:171], v[192:195], v[8:11], v[168:171]
	v_fma_f32 v220, v164, v179, -v180
	v_fma_f32 v221, v165, v179, -v180
	v_mfma_f32_16x16x32_bf16 v[172:175], v[192:195], v[40:43], v[172:175]
	v_fma_f32 v222, v166, v179, -v180
	v_fma_f32 v223, v167, v179, -v180
	v_mfma_f32_16x16x32_bf16 v[168:171], v[196:199], v[12:15], v[168:171]
	v_exp_f32_e32 v220, v220
	v_exp_f32_e32 v221, v221
	v_mfma_f32_16x16x32_bf16 v[172:175], v[196:199], v[44:47], v[172:175]
	v_exp_f32_e32 v222, v222
	v_exp_f32_e32 v223, v223
	v_mfma_f32_16x16x32_bf16 v[168:171], v[200:203], v[16:19], v[168:171]
	v_add_f32_e32 v176, v176, v216
	v_add_f32_e32 v176, v176, v217
	v_mfma_f32_16x16x32_bf16 v[172:175], v[200:203], v[48:51], v[172:175]
	v_cvt_pk_bf16_f32 v72, v216, v217
	v_add_f32_e32 v176, v176, v218
	v_mfma_f32_16x16x32_bf16 v[168:171], v[204:207], v[20:23], v[168:171]
	v_add_f32_e32 v176, v176, v219
	v_cvt_pk_bf16_f32 v73, v218, v219
	v_mfma_f32_16x16x32_bf16 v[172:175], v[204:207], v[52:55], v[172:175]
	v_add_f32_e32 v177, v177, v220
	v_add_f32_e32 v177, v177, v221
	v_mfma_f32_16x16x32_bf16 v[168:171], v[208:211], v[24:27], v[168:171]
	v_cvt_pk_bf16_f32 v104, v220, v221
	v_add_f32_e32 v177, v177, v222
	v_mfma_f32_16x16x32_bf16 v[172:175], v[208:211], v[56:59], v[172:175]
	v_add_f32_e32 v177, v177, v223
	v_cvt_pk_bf16_f32 v105, v222, v223
	v_mfma_f32_16x16x32_bf16 v[168:171], v[212:215], v[28:31], v[168:171]
	v_mfma_f32_16x16x32_bf16 v[172:175], v[212:215], v[60:63], v[172:175]
	s_waitcnt lgkmcnt(0)
	v_add_u32_e32 v233, 60928, v233
	ds_read_b128 v[184:187], v233 offset:0
	ds_read_b128 v[188:191], v233 offset:64
	ds_read_b128 v[192:195], v233 offset:128
	ds_read_b128 v[196:199], v233 offset:192
	ds_read_b128 v[200:203], v233 offset:256
	ds_read_b128 v[204:207], v233 offset:320
	ds_read_b128 v[208:211], v233 offset:384
	ds_read_b128 v[212:215], v233 offset:448
	v_mfma_f32_16x16x32_bf16 v[160:163], v[128:131], v[0:3], 0
	v_fma_f32 v216, v168, v178, -v180
	v_fma_f32 v217, v169, v178, -v180
	v_mfma_f32_16x16x32_bf16 v[164:167], v[128:131], v[32:35], 0
	v_fma_f32 v218, v170, v178, -v180
	v_fma_f32 v219, v171, v178, -v180
	v_mfma_f32_16x16x32_bf16 v[160:163], v[132:135], v[4:7], v[160:163]
	v_exp_f32_e32 v216, v216
	v_exp_f32_e32 v217, v217
	v_mfma_f32_16x16x32_bf16 v[164:167], v[132:135], v[36:39], v[164:167]
	v_exp_f32_e32 v218, v218
	v_exp_f32_e32 v219, v219
	v_mfma_f32_16x16x32_bf16 v[160:163], v[136:139], v[8:11], v[160:163]
	v_fma_f32 v220, v172, v179, -v180
	v_fma_f32 v221, v173, v179, -v180
	v_mfma_f32_16x16x32_bf16 v[164:167], v[136:139], v[40:43], v[164:167]
	v_fma_f32 v222, v174, v179, -v180
	v_fma_f32 v223, v175, v179, -v180
	v_mfma_f32_16x16x32_bf16 v[160:163], v[140:143], v[12:15], v[160:163]
	v_exp_f32_e32 v220, v220
	v_exp_f32_e32 v221, v221
	v_mfma_f32_16x16x32_bf16 v[164:167], v[140:143], v[44:47], v[164:167]
	v_exp_f32_e32 v222, v222
	v_exp_f32_e32 v223, v223
	v_mfma_f32_16x16x32_bf16 v[160:163], v[144:147], v[16:19], v[160:163]
	v_add_f32_e32 v176, v176, v216
	v_add_f32_e32 v176, v176, v217
	v_mfma_f32_16x16x32_bf16 v[164:167], v[144:147], v[48:51], v[164:167]
	v_cvt_pk_bf16_f32 v74, v216, v217
	v_add_f32_e32 v176, v176, v218
	v_mfma_f32_16x16x32_bf16 v[160:163], v[148:151], v[20:23], v[160:163]
	v_add_f32_e32 v176, v176, v219
	v_cvt_pk_bf16_f32 v75, v218, v219
	v_mfma_f32_16x16x32_bf16 v[164:167], v[148:151], v[52:55], v[164:167]
	v_add_f32_e32 v177, v177, v220
	v_add_f32_e32 v177, v177, v221
	v_mfma_f32_16x16x32_bf16 v[160:163], v[152:155], v[24:27], v[160:163]
	v_cvt_pk_bf16_f32 v106, v220, v221
	v_add_f32_e32 v177, v177, v222
	v_mfma_f32_16x16x32_bf16 v[164:167], v[152:155], v[56:59], v[164:167]
	v_add_f32_e32 v177, v177, v223
	v_cvt_pk_bf16_f32 v107, v222, v223
	v_mfma_f32_16x16x32_bf16 v[160:163], v[156:159], v[28:31], v[160:163]
	v_mfma_f32_16x16x32_bf16 v[164:167], v[156:159], v[60:63], v[164:167]
	s_waitcnt lgkmcnt(0)
	ds_read_b128 v[128:131], v233 offset:8704
	ds_read_b128 v[132:135], v233 offset:8768
	ds_read_b128 v[136:139], v233 offset:8832
	ds_read_b128 v[140:143], v233 offset:8896
	ds_read_b128 v[144:147], v233 offset:8960
	ds_read_b128 v[148:151], v233 offset:9024
	ds_read_b128 v[152:155], v233 offset:9088
	ds_read_b128 v[156:159], v233 offset:9152
	v_mfma_f32_16x16x32_bf16 v[168:171], v[184:187], v[0:3], 0
	v_fma_f32 v216, v160, v178, -v180
	v_fma_f32 v217, v161, v178, -v180
	v_mfma_f32_16x16x32_bf16 v[172:175], v[184:187], v[32:35], 0
	v_fma_f32 v218, v162, v178, -v180
	v_fma_f32 v219, v163, v178, -v180
	v_mfma_f32_16x16x32_bf16 v[168:171], v[188:191], v[4:7], v[168:171]
	v_exp_f32_e32 v216, v216
	v_exp_f32_e32 v217, v217
	v_mfma_f32_16x16x32_bf16 v[172:175], v[188:191], v[36:39], v[172:175]
	v_exp_f32_e32 v218, v218
	v_exp_f32_e32 v219, v219
	v_mfma_f32_16x16x32_bf16 v[168:171], v[192:195], v[8:11], v[168:171]
	v_fma_f32 v220, v164, v179, -v180
	v_fma_f32 v221, v165, v179, -v180
	v_mfma_f32_16x16x32_bf16 v[172:175], v[192:195], v[40:43], v[172:175]
	v_fma_f32 v222, v166, v179, -v180
	v_fma_f32 v223, v167, v179, -v180
	v_mfma_f32_16x16x32_bf16 v[168:171], v[196:199], v[12:15], v[168:171]
	v_exp_f32_e32 v220, v220
	v_exp_f32_e32 v221, v221
	v_mfma_f32_16x16x32_bf16 v[172:175], v[196:199], v[44:47], v[172:175]
	v_exp_f32_e32 v222, v222
	v_exp_f32_e32 v223, v223
	v_mfma_f32_16x16x32_bf16 v[168:171], v[200:203], v[16:19], v[168:171]
	v_add_f32_e32 v176, v176, v216
	v_add_f32_e32 v176, v176, v217
	v_mfma_f32_16x16x32_bf16 v[172:175], v[200:203], v[48:51], v[172:175]
	v_cvt_pk_bf16_f32 v76, v216, v217
	v_add_f32_e32 v176, v176, v218
	v_mfma_f32_16x16x32_bf16 v[168:171], v[204:207], v[20:23], v[168:171]
	v_add_f32_e32 v176, v176, v219
	v_cvt_pk_bf16_f32 v77, v218, v219
	v_mfma_f32_16x16x32_bf16 v[172:175], v[204:207], v[52:55], v[172:175]
	v_add_f32_e32 v177, v177, v220
	v_add_f32_e32 v177, v177, v221
	v_mfma_f32_16x16x32_bf16 v[168:171], v[208:211], v[24:27], v[168:171]
	v_cvt_pk_bf16_f32 v108, v220, v221
	v_add_f32_e32 v177, v177, v222
	v_mfma_f32_16x16x32_bf16 v[172:175], v[208:211], v[56:59], v[172:175]
	v_add_f32_e32 v177, v177, v223
	v_cvt_pk_bf16_f32 v109, v222, v223
	v_mfma_f32_16x16x32_bf16 v[168:171], v[212:215], v[28:31], v[168:171]
	v_mfma_f32_16x16x32_bf16 v[172:175], v[212:215], v[60:63], v[172:175]
	s_waitcnt lgkmcnt(0)
	ds_read_b128 v[184:187], v233 offset:17408
	ds_read_b128 v[188:191], v233 offset:17472
	ds_read_b128 v[192:195], v233 offset:17536
	ds_read_b128 v[196:199], v233 offset:17600
	ds_read_b128 v[200:203], v233 offset:17664
	ds_read_b128 v[204:207], v233 offset:17728
	ds_read_b128 v[208:211], v233 offset:17792
	ds_read_b128 v[212:215], v233 offset:17856
	v_mfma_f32_16x16x32_bf16 v[160:163], v[128:131], v[0:3], 0
	v_fma_f32 v216, v168, v178, -v180
	v_fma_f32 v217, v169, v178, -v180
	v_mfma_f32_16x16x32_bf16 v[164:167], v[128:131], v[32:35], 0
	v_fma_f32 v218, v170, v178, -v180
	v_fma_f32 v219, v171, v178, -v180
	v_mfma_f32_16x16x32_bf16 v[160:163], v[132:135], v[4:7], v[160:163]
	v_exp_f32_e32 v216, v216
	v_exp_f32_e32 v217, v217
	v_mfma_f32_16x16x32_bf16 v[164:167], v[132:135], v[36:39], v[164:167]
	v_exp_f32_e32 v218, v218
	v_exp_f32_e32 v219, v219
	v_mfma_f32_16x16x32_bf16 v[160:163], v[136:139], v[8:11], v[160:163]
	v_fma_f32 v220, v172, v179, -v180
	v_fma_f32 v221, v173, v179, -v180
	v_mfma_f32_16x16x32_bf16 v[164:167], v[136:139], v[40:43], v[164:167]
	v_fma_f32 v222, v174, v179, -v180
	v_fma_f32 v223, v175, v179, -v180
	v_mfma_f32_16x16x32_bf16 v[160:163], v[140:143], v[12:15], v[160:163]
	v_exp_f32_e32 v220, v220
	v_exp_f32_e32 v221, v221
	v_mfma_f32_16x16x32_bf16 v[164:167], v[140:143], v[44:47], v[164:167]
	v_exp_f32_e32 v222, v222
	v_exp_f32_e32 v223, v223
	v_mfma_f32_16x16x32_bf16 v[160:163], v[144:147], v[16:19], v[160:163]
	v_add_f32_e32 v176, v176, v216
	v_add_f32_e32 v176, v176, v217
	v_mfma_f32_16x16x32_bf16 v[164:167], v[144:147], v[48:51], v[164:167]
	v_cvt_pk_bf16_f32 v78, v216, v217
	v_add_f32_e32 v176, v176, v218
	v_mfma_f32_16x16x32_bf16 v[160:163], v[148:151], v[20:23], v[160:163]
	v_add_f32_e32 v176, v176, v219
	v_cvt_pk_bf16_f32 v79, v218, v219
	v_mfma_f32_16x16x32_bf16 v[164:167], v[148:151], v[52:55], v[164:167]
	v_add_f32_e32 v177, v177, v220
	v_add_f32_e32 v177, v177, v221
	v_mfma_f32_16x16x32_bf16 v[160:163], v[152:155], v[24:27], v[160:163]
	v_cvt_pk_bf16_f32 v110, v220, v221
	v_add_f32_e32 v177, v177, v222
	v_mfma_f32_16x16x32_bf16 v[164:167], v[152:155], v[56:59], v[164:167]
	v_add_f32_e32 v177, v177, v223
	v_cvt_pk_bf16_f32 v111, v222, v223
	v_mfma_f32_16x16x32_bf16 v[160:163], v[156:159], v[28:31], v[160:163]
	v_mfma_f32_16x16x32_bf16 v[164:167], v[156:159], v[60:63], v[164:167]
	s_waitcnt lgkmcnt(0)
	ds_read_b128 v[128:131], v233 offset:26112
	ds_read_b128 v[132:135], v233 offset:26176
	ds_read_b128 v[136:139], v233 offset:26240
	ds_read_b128 v[140:143], v233 offset:26304
	ds_read_b128 v[144:147], v233 offset:26368
	ds_read_b128 v[148:151], v233 offset:26432
	ds_read_b128 v[152:155], v233 offset:26496
	ds_read_b128 v[156:159], v233 offset:26560
	v_mfma_f32_16x16x32_bf16 v[168:171], v[184:187], v[0:3], 0
	v_fma_f32 v216, v160, v178, -v180
	v_fma_f32 v217, v161, v178, -v180
	v_mfma_f32_16x16x32_bf16 v[172:175], v[184:187], v[32:35], 0
	v_fma_f32 v218, v162, v178, -v180
	v_fma_f32 v219, v163, v178, -v180
	v_mfma_f32_16x16x32_bf16 v[168:171], v[188:191], v[4:7], v[168:171]
	v_exp_f32_e32 v216, v216
	v_exp_f32_e32 v217, v217
	v_mfma_f32_16x16x32_bf16 v[172:175], v[188:191], v[36:39], v[172:175]
	v_exp_f32_e32 v218, v218
	v_exp_f32_e32 v219, v219
	v_mfma_f32_16x16x32_bf16 v[168:171], v[192:195], v[8:11], v[168:171]
	v_fma_f32 v220, v164, v179, -v180
	v_fma_f32 v221, v165, v179, -v180
	v_mfma_f32_16x16x32_bf16 v[172:175], v[192:195], v[40:43], v[172:175]
	v_fma_f32 v222, v166, v179, -v180
	v_fma_f32 v223, v167, v179, -v180
	v_mfma_f32_16x16x32_bf16 v[168:171], v[196:199], v[12:15], v[168:171]
	v_exp_f32_e32 v220, v220
	v_exp_f32_e32 v221, v221
	v_mfma_f32_16x16x32_bf16 v[172:175], v[196:199], v[44:47], v[172:175]
	v_exp_f32_e32 v222, v222
	v_exp_f32_e32 v223, v223
	v_mfma_f32_16x16x32_bf16 v[168:171], v[200:203], v[16:19], v[168:171]
	v_add_f32_e32 v176, v176, v216
	v_add_f32_e32 v176, v176, v217
	v_mfma_f32_16x16x32_bf16 v[172:175], v[200:203], v[48:51], v[172:175]
	v_cvt_pk_bf16_f32 v80, v216, v217
	v_add_f32_e32 v176, v176, v218
	v_mfma_f32_16x16x32_bf16 v[168:171], v[204:207], v[20:23], v[168:171]
	v_add_f32_e32 v176, v176, v219
	v_cvt_pk_bf16_f32 v81, v218, v219
	v_mfma_f32_16x16x32_bf16 v[172:175], v[204:207], v[52:55], v[172:175]
	v_add_f32_e32 v177, v177, v220
	v_add_f32_e32 v177, v177, v221
	v_mfma_f32_16x16x32_bf16 v[168:171], v[208:211], v[24:27], v[168:171]
	v_cvt_pk_bf16_f32 v112, v220, v221
	v_add_f32_e32 v177, v177, v222
	v_mfma_f32_16x16x32_bf16 v[172:175], v[208:211], v[56:59], v[172:175]
	v_add_f32_e32 v177, v177, v223
	v_cvt_pk_bf16_f32 v113, v222, v223
	v_mfma_f32_16x16x32_bf16 v[168:171], v[212:215], v[28:31], v[168:171]
	v_mfma_f32_16x16x32_bf16 v[172:175], v[212:215], v[60:63], v[172:175]
	s_waitcnt lgkmcnt(0)
	ds_read_b128 v[184:187], v233 offset:34816
	ds_read_b128 v[188:191], v233 offset:34880
	ds_read_b128 v[192:195], v233 offset:34944
	ds_read_b128 v[196:199], v233 offset:35008
	ds_read_b128 v[200:203], v233 offset:35072
	ds_read_b128 v[204:207], v233 offset:35136
	ds_read_b128 v[208:211], v233 offset:35200
	ds_read_b128 v[212:215], v233 offset:35264
	v_mfma_f32_16x16x32_bf16 v[160:163], v[128:131], v[0:3], 0
	v_fma_f32 v216, v168, v178, -v180
	v_fma_f32 v217, v169, v178, -v180
	v_mfma_f32_16x16x32_bf16 v[164:167], v[128:131], v[32:35], 0
	v_fma_f32 v218, v170, v178, -v180
	v_fma_f32 v219, v171, v178, -v180
	v_mfma_f32_16x16x32_bf16 v[160:163], v[132:135], v[4:7], v[160:163]
	v_exp_f32_e32 v216, v216
	v_exp_f32_e32 v217, v217
	v_mfma_f32_16x16x32_bf16 v[164:167], v[132:135], v[36:39], v[164:167]
	v_exp_f32_e32 v218, v218
	v_exp_f32_e32 v219, v219
	v_mfma_f32_16x16x32_bf16 v[160:163], v[136:139], v[8:11], v[160:163]
	v_fma_f32 v220, v172, v179, -v180
	v_fma_f32 v221, v173, v179, -v180
	v_mfma_f32_16x16x32_bf16 v[164:167], v[136:139], v[40:43], v[164:167]
	v_fma_f32 v222, v174, v179, -v180
	v_fma_f32 v223, v175, v179, -v180
	v_mfma_f32_16x16x32_bf16 v[160:163], v[140:143], v[12:15], v[160:163]
	v_exp_f32_e32 v220, v220
	v_exp_f32_e32 v221, v221
	v_mfma_f32_16x16x32_bf16 v[164:167], v[140:143], v[44:47], v[164:167]
	v_exp_f32_e32 v222, v222
	v_exp_f32_e32 v223, v223
	v_mfma_f32_16x16x32_bf16 v[160:163], v[144:147], v[16:19], v[160:163]
	v_add_f32_e32 v176, v176, v216
	v_add_f32_e32 v176, v176, v217
	v_mfma_f32_16x16x32_bf16 v[164:167], v[144:147], v[48:51], v[164:167]
	v_cvt_pk_bf16_f32 v82, v216, v217
	v_add_f32_e32 v176, v176, v218
	v_mfma_f32_16x16x32_bf16 v[160:163], v[148:151], v[20:23], v[160:163]
	v_add_f32_e32 v176, v176, v219
	v_cvt_pk_bf16_f32 v83, v218, v219
	v_mfma_f32_16x16x32_bf16 v[164:167], v[148:151], v[52:55], v[164:167]
	v_add_f32_e32 v177, v177, v220
	v_add_f32_e32 v177, v177, v221
	v_mfma_f32_16x16x32_bf16 v[160:163], v[152:155], v[24:27], v[160:163]
	v_cvt_pk_bf16_f32 v114, v220, v221
	v_add_f32_e32 v177, v177, v222
	v_mfma_f32_16x16x32_bf16 v[164:167], v[152:155], v[56:59], v[164:167]
	v_add_f32_e32 v177, v177, v223
	v_cvt_pk_bf16_f32 v115, v222, v223
	v_mfma_f32_16x16x32_bf16 v[160:163], v[156:159], v[28:31], v[160:163]
	v_mfma_f32_16x16x32_bf16 v[164:167], v[156:159], v[60:63], v[164:167]
	s_waitcnt lgkmcnt(0)
	ds_read_b128 v[128:131], v233 offset:43520
	ds_read_b128 v[132:135], v233 offset:43584
	ds_read_b128 v[136:139], v233 offset:43648
	ds_read_b128 v[140:143], v233 offset:43712
	ds_read_b128 v[144:147], v233 offset:43776
	ds_read_b128 v[148:151], v233 offset:43840
	ds_read_b128 v[152:155], v233 offset:43904
	ds_read_b128 v[156:159], v233 offset:43968
	v_mfma_f32_16x16x32_bf16 v[168:171], v[184:187], v[0:3], 0
	v_fma_f32 v216, v160, v178, -v180
	v_fma_f32 v217, v161, v178, -v180
	v_mfma_f32_16x16x32_bf16 v[172:175], v[184:187], v[32:35], 0
	v_fma_f32 v218, v162, v178, -v180
	v_fma_f32 v219, v163, v178, -v180
	v_mfma_f32_16x16x32_bf16 v[168:171], v[188:191], v[4:7], v[168:171]
	v_exp_f32_e32 v216, v216
	v_exp_f32_e32 v217, v217
	v_mfma_f32_16x16x32_bf16 v[172:175], v[188:191], v[36:39], v[172:175]
	v_exp_f32_e32 v218, v218
	v_exp_f32_e32 v219, v219
	v_mfma_f32_16x16x32_bf16 v[168:171], v[192:195], v[8:11], v[168:171]
	v_fma_f32 v220, v164, v179, -v180
	v_fma_f32 v221, v165, v179, -v180
	v_mfma_f32_16x16x32_bf16 v[172:175], v[192:195], v[40:43], v[172:175]
	v_fma_f32 v222, v166, v179, -v180
	v_fma_f32 v223, v167, v179, -v180
	v_mfma_f32_16x16x32_bf16 v[168:171], v[196:199], v[12:15], v[168:171]
	v_exp_f32_e32 v220, v220
	v_exp_f32_e32 v221, v221
	v_mfma_f32_16x16x32_bf16 v[172:175], v[196:199], v[44:47], v[172:175]
	v_exp_f32_e32 v222, v222
	v_exp_f32_e32 v223, v223
	v_mfma_f32_16x16x32_bf16 v[168:171], v[200:203], v[16:19], v[168:171]
	v_add_f32_e32 v176, v176, v216
	v_add_f32_e32 v176, v176, v217
	v_mfma_f32_16x16x32_bf16 v[172:175], v[200:203], v[48:51], v[172:175]
	v_cvt_pk_bf16_f32 v84, v216, v217
	v_add_f32_e32 v176, v176, v218
	v_mfma_f32_16x16x32_bf16 v[168:171], v[204:207], v[20:23], v[168:171]
	v_add_f32_e32 v176, v176, v219
	v_cvt_pk_bf16_f32 v85, v218, v219
	v_mfma_f32_16x16x32_bf16 v[172:175], v[204:207], v[52:55], v[172:175]
	v_add_f32_e32 v177, v177, v220
	v_add_f32_e32 v177, v177, v221
	v_mfma_f32_16x16x32_bf16 v[168:171], v[208:211], v[24:27], v[168:171]
	v_cvt_pk_bf16_f32 v116, v220, v221
	v_add_f32_e32 v177, v177, v222
	v_mfma_f32_16x16x32_bf16 v[172:175], v[208:211], v[56:59], v[172:175]
	v_add_f32_e32 v177, v177, v223
	v_cvt_pk_bf16_f32 v117, v222, v223
	v_mfma_f32_16x16x32_bf16 v[168:171], v[212:215], v[28:31], v[168:171]
	v_mfma_f32_16x16x32_bf16 v[172:175], v[212:215], v[60:63], v[172:175]
	s_waitcnt lgkmcnt(0)
	ds_read_b128 v[184:187], v233 offset:52224
	ds_read_b128 v[188:191], v233 offset:52288
	ds_read_b128 v[192:195], v233 offset:52352
	ds_read_b128 v[196:199], v233 offset:52416
	ds_read_b128 v[200:203], v233 offset:52480
	ds_read_b128 v[204:207], v233 offset:52544
	ds_read_b128 v[208:211], v233 offset:52608
	ds_read_b128 v[212:215], v233 offset:52672
	v_mfma_f32_16x16x32_bf16 v[160:163], v[128:131], v[0:3], 0
	v_fma_f32 v216, v168, v178, -v180
	v_fma_f32 v217, v169, v178, -v180
	v_mfma_f32_16x16x32_bf16 v[164:167], v[128:131], v[32:35], 0
	v_fma_f32 v218, v170, v178, -v180
	v_fma_f32 v219, v171, v178, -v180
	v_mfma_f32_16x16x32_bf16 v[160:163], v[132:135], v[4:7], v[160:163]
	v_exp_f32_e32 v216, v216
	v_exp_f32_e32 v217, v217
	v_mfma_f32_16x16x32_bf16 v[164:167], v[132:135], v[36:39], v[164:167]
	v_exp_f32_e32 v218, v218
	v_exp_f32_e32 v219, v219
	v_mfma_f32_16x16x32_bf16 v[160:163], v[136:139], v[8:11], v[160:163]
	v_fma_f32 v220, v172, v179, -v180
	v_fma_f32 v221, v173, v179, -v180
	v_mfma_f32_16x16x32_bf16 v[164:167], v[136:139], v[40:43], v[164:167]
	v_fma_f32 v222, v174, v179, -v180
	v_fma_f32 v223, v175, v179, -v180
	v_mfma_f32_16x16x32_bf16 v[160:163], v[140:143], v[12:15], v[160:163]
	v_exp_f32_e32 v220, v220
	v_exp_f32_e32 v221, v221
	v_mfma_f32_16x16x32_bf16 v[164:167], v[140:143], v[44:47], v[164:167]
	v_exp_f32_e32 v222, v222
	v_exp_f32_e32 v223, v223
	v_mfma_f32_16x16x32_bf16 v[160:163], v[144:147], v[16:19], v[160:163]
	v_add_f32_e32 v176, v176, v216
	v_add_f32_e32 v176, v176, v217
	v_mfma_f32_16x16x32_bf16 v[164:167], v[144:147], v[48:51], v[164:167]
	v_cvt_pk_bf16_f32 v86, v216, v217
	v_add_f32_e32 v176, v176, v218
	v_mfma_f32_16x16x32_bf16 v[160:163], v[148:151], v[20:23], v[160:163]
	v_add_f32_e32 v176, v176, v219
	v_cvt_pk_bf16_f32 v87, v218, v219
	v_mfma_f32_16x16x32_bf16 v[164:167], v[148:151], v[52:55], v[164:167]
	v_add_f32_e32 v177, v177, v220
	v_add_f32_e32 v177, v177, v221
	v_mfma_f32_16x16x32_bf16 v[160:163], v[152:155], v[24:27], v[160:163]
	v_cvt_pk_bf16_f32 v118, v220, v221
	v_add_f32_e32 v177, v177, v222
	v_mfma_f32_16x16x32_bf16 v[164:167], v[152:155], v[56:59], v[164:167]
	v_add_f32_e32 v177, v177, v223
	v_cvt_pk_bf16_f32 v119, v222, v223
	v_mfma_f32_16x16x32_bf16 v[160:163], v[156:159], v[28:31], v[160:163]
	v_mfma_f32_16x16x32_bf16 v[164:167], v[156:159], v[60:63], v[164:167]
	s_waitcnt lgkmcnt(0)
	v_add_u32_e32 v233, 60928, v233
	ds_read_b128 v[128:131], v233 offset:0
	ds_read_b128 v[132:135], v233 offset:64
	ds_read_b128 v[136:139], v233 offset:128
	ds_read_b128 v[140:143], v233 offset:192
	ds_read_b128 v[144:147], v233 offset:256
	ds_read_b128 v[148:151], v233 offset:320
	ds_read_b128 v[152:155], v233 offset:384
	ds_read_b128 v[156:159], v233 offset:448
	v_mfma_f32_16x16x32_bf16 v[168:171], v[184:187], v[0:3], 0
	v_fma_f32 v216, v160, v178, -v180
	v_fma_f32 v217, v161, v178, -v180
	v_mfma_f32_16x16x32_bf16 v[172:175], v[184:187], v[32:35], 0
	v_fma_f32 v218, v162, v178, -v180
	v_fma_f32 v219, v163, v178, -v180
	v_mfma_f32_16x16x32_bf16 v[168:171], v[188:191], v[4:7], v[168:171]
	v_exp_f32_e32 v216, v216
	v_exp_f32_e32 v217, v217
	v_mfma_f32_16x16x32_bf16 v[172:175], v[188:191], v[36:39], v[172:175]
	v_exp_f32_e32 v218, v218
	v_exp_f32_e32 v219, v219
	v_mfma_f32_16x16x32_bf16 v[168:171], v[192:195], v[8:11], v[168:171]
	v_fma_f32 v220, v164, v179, -v180
	v_fma_f32 v221, v165, v179, -v180
	v_mfma_f32_16x16x32_bf16 v[172:175], v[192:195], v[40:43], v[172:175]
	v_fma_f32 v222, v166, v179, -v180
	v_fma_f32 v223, v167, v179, -v180
	v_mfma_f32_16x16x32_bf16 v[168:171], v[196:199], v[12:15], v[168:171]
	v_exp_f32_e32 v220, v220
	v_exp_f32_e32 v221, v221
	v_mfma_f32_16x16x32_bf16 v[172:175], v[196:199], v[44:47], v[172:175]
	v_exp_f32_e32 v222, v222
	v_exp_f32_e32 v223, v223
	v_mfma_f32_16x16x32_bf16 v[168:171], v[200:203], v[16:19], v[168:171]
	v_add_f32_e32 v176, v176, v216
	v_add_f32_e32 v176, v176, v217
	v_mfma_f32_16x16x32_bf16 v[172:175], v[200:203], v[48:51], v[172:175]
	v_cvt_pk_bf16_f32 v88, v216, v217
	v_add_f32_e32 v176, v176, v218
	v_mfma_f32_16x16x32_bf16 v[168:171], v[204:207], v[20:23], v[168:171]
	v_add_f32_e32 v176, v176, v219
	v_cvt_pk_bf16_f32 v89, v218, v219
	v_mfma_f32_16x16x32_bf16 v[172:175], v[204:207], v[52:55], v[172:175]
	v_add_f32_e32 v177, v177, v220
	v_add_f32_e32 v177, v177, v221
	v_mfma_f32_16x16x32_bf16 v[168:171], v[208:211], v[24:27], v[168:171]
	v_cvt_pk_bf16_f32 v120, v220, v221
	v_add_f32_e32 v177, v177, v222
	v_mfma_f32_16x16x32_bf16 v[172:175], v[208:211], v[56:59], v[172:175]
	v_add_f32_e32 v177, v177, v223
	v_cvt_pk_bf16_f32 v121, v222, v223
	v_mfma_f32_16x16x32_bf16 v[168:171], v[212:215], v[28:31], v[168:171]
	v_mfma_f32_16x16x32_bf16 v[172:175], v[212:215], v[60:63], v[172:175]
	s_waitcnt lgkmcnt(0)
	ds_read_b128 v[184:187], v233 offset:8704
	ds_read_b128 v[188:191], v233 offset:8768
	ds_read_b128 v[192:195], v233 offset:8832
	ds_read_b128 v[196:199], v233 offset:8896
	ds_read_b128 v[200:203], v233 offset:8960
	ds_read_b128 v[204:207], v233 offset:9024
	ds_read_b128 v[208:211], v233 offset:9088
	ds_read_b128 v[212:215], v233 offset:9152
	v_mfma_f32_16x16x32_bf16 v[160:163], v[128:131], v[0:3], 0
	v_fma_f32 v216, v168, v178, -v180
	v_fma_f32 v217, v169, v178, -v180
	v_mfma_f32_16x16x32_bf16 v[164:167], v[128:131], v[32:35], 0
	v_fma_f32 v218, v170, v178, -v180
	v_fma_f32 v219, v171, v178, -v180
	v_mfma_f32_16x16x32_bf16 v[160:163], v[132:135], v[4:7], v[160:163]
	v_exp_f32_e32 v216, v216
	v_exp_f32_e32 v217, v217
	v_mfma_f32_16x16x32_bf16 v[164:167], v[132:135], v[36:39], v[164:167]
	v_exp_f32_e32 v218, v218
	v_exp_f32_e32 v219, v219
	v_mfma_f32_16x16x32_bf16 v[160:163], v[136:139], v[8:11], v[160:163]
	v_fma_f32 v220, v172, v179, -v180
	v_fma_f32 v221, v173, v179, -v180
	v_mfma_f32_16x16x32_bf16 v[164:167], v[136:139], v[40:43], v[164:167]
	v_fma_f32 v222, v174, v179, -v180
	v_fma_f32 v223, v175, v179, -v180
	v_mfma_f32_16x16x32_bf16 v[160:163], v[140:143], v[12:15], v[160:163]
	v_exp_f32_e32 v220, v220
	v_exp_f32_e32 v221, v221
	v_mfma_f32_16x16x32_bf16 v[164:167], v[140:143], v[44:47], v[164:167]
	v_exp_f32_e32 v222, v222
	v_exp_f32_e32 v223, v223
	v_mfma_f32_16x16x32_bf16 v[160:163], v[144:147], v[16:19], v[160:163]
	v_add_f32_e32 v176, v176, v216
	v_add_f32_e32 v176, v176, v217
	v_mfma_f32_16x16x32_bf16 v[164:167], v[144:147], v[48:51], v[164:167]
	v_cvt_pk_bf16_f32 v90, v216, v217
	v_add_f32_e32 v176, v176, v218
	v_mfma_f32_16x16x32_bf16 v[160:163], v[148:151], v[20:23], v[160:163]
	v_add_f32_e32 v176, v176, v219
	v_cvt_pk_bf16_f32 v91, v218, v219
	v_mfma_f32_16x16x32_bf16 v[164:167], v[148:151], v[52:55], v[164:167]
	v_add_f32_e32 v177, v177, v220
	v_add_f32_e32 v177, v177, v221
	v_mfma_f32_16x16x32_bf16 v[160:163], v[152:155], v[24:27], v[160:163]
	v_cvt_pk_bf16_f32 v122, v220, v221
	v_add_f32_e32 v177, v177, v222
	v_mfma_f32_16x16x32_bf16 v[164:167], v[152:155], v[56:59], v[164:167]
	v_add_f32_e32 v177, v177, v223
	v_cvt_pk_bf16_f32 v123, v222, v223
	v_mfma_f32_16x16x32_bf16 v[160:163], v[156:159], v[28:31], v[160:163]
	v_mfma_f32_16x16x32_bf16 v[164:167], v[156:159], v[60:63], v[164:167]
	s_waitcnt lgkmcnt(0)
	s_nop 6
	v_mfma_f32_16x16x32_bf16 v[168:171], v[184:187], v[0:3], 0
	v_fma_f32 v216, v160, v178, -v180
	v_fma_f32 v217, v161, v178, -v180
	v_mfma_f32_16x16x32_bf16 v[172:175], v[184:187], v[32:35], 0
	v_fma_f32 v218, v162, v178, -v180
	v_fma_f32 v219, v163, v178, -v180
	v_mfma_f32_16x16x32_bf16 v[168:171], v[188:191], v[4:7], v[168:171]
	v_exp_f32_e32 v216, v216
	v_exp_f32_e32 v217, v217
	v_mfma_f32_16x16x32_bf16 v[172:175], v[188:191], v[36:39], v[172:175]
	v_exp_f32_e32 v218, v218
	v_exp_f32_e32 v219, v219
	v_mfma_f32_16x16x32_bf16 v[168:171], v[192:195], v[8:11], v[168:171]
	v_fma_f32 v220, v164, v179, -v180
	v_fma_f32 v221, v165, v179, -v180
	v_mfma_f32_16x16x32_bf16 v[172:175], v[192:195], v[40:43], v[172:175]
	v_fma_f32 v222, v166, v179, -v180
	v_fma_f32 v223, v167, v179, -v180
	v_mfma_f32_16x16x32_bf16 v[168:171], v[196:199], v[12:15], v[168:171]
	v_exp_f32_e32 v220, v220
	v_exp_f32_e32 v221, v221
	v_mfma_f32_16x16x32_bf16 v[172:175], v[196:199], v[44:47], v[172:175]
	v_exp_f32_e32 v222, v222
	v_exp_f32_e32 v223, v223
	v_mfma_f32_16x16x32_bf16 v[168:171], v[200:203], v[16:19], v[168:171]
	v_add_f32_e32 v176, v176, v216
	v_add_f32_e32 v176, v176, v217
	v_mfma_f32_16x16x32_bf16 v[172:175], v[200:203], v[48:51], v[172:175]
	v_cvt_pk_bf16_f32 v92, v216, v217
	v_add_f32_e32 v176, v176, v218
	v_mfma_f32_16x16x32_bf16 v[168:171], v[204:207], v[20:23], v[168:171]
	v_add_f32_e32 v176, v176, v219
	v_cvt_pk_bf16_f32 v93, v218, v219
	v_mfma_f32_16x16x32_bf16 v[172:175], v[204:207], v[52:55], v[172:175]
	v_add_f32_e32 v177, v177, v220
	v_add_f32_e32 v177, v177, v221
	v_mfma_f32_16x16x32_bf16 v[168:171], v[208:211], v[24:27], v[168:171]
	v_cvt_pk_bf16_f32 v124, v220, v221
	v_add_f32_e32 v177, v177, v222
	v_mfma_f32_16x16x32_bf16 v[172:175], v[208:211], v[56:59], v[172:175]
	v_add_f32_e32 v177, v177, v223
	v_cvt_pk_bf16_f32 v125, v222, v223
	v_mfma_f32_16x16x32_bf16 v[168:171], v[212:215], v[28:31], v[168:171]
	v_mfma_f32_16x16x32_bf16 v[172:175], v[212:215], v[60:63], v[172:175]
	s_nop 7
	v_fma_f32 v216, v168, v178, -v180
	v_fma_f32 v217, v169, v178, -v180
	v_fma_f32 v218, v170, v178, -v180
	v_fma_f32 v219, v171, v178, -v180
	v_exp_f32_e32 v216, v216
	v_exp_f32_e32 v217, v217
	v_exp_f32_e32 v218, v218
	v_exp_f32_e32 v219, v219
	v_fma_f32 v220, v172, v179, -v180
	v_fma_f32 v221, v173, v179, -v180
	v_fma_f32 v222, v174, v179, -v180
	v_fma_f32 v223, v175, v179, -v180
	v_exp_f32_e32 v220, v220
	v_exp_f32_e32 v221, v221
	v_exp_f32_e32 v222, v222
	v_exp_f32_e32 v223, v223
	v_add_f32_e32 v176, v176, v216
	v_add_f32_e32 v176, v176, v217
	v_cvt_pk_bf16_f32 v94, v216, v217
	v_add_f32_e32 v176, v176, v218
	v_add_f32_e32 v176, v176, v219
	v_cvt_pk_bf16_f32 v95, v218, v219
	v_add_f32_e32 v177, v177, v220
	v_add_f32_e32 v177, v177, v221
	v_cvt_pk_bf16_f32 v126, v220, v221
	v_add_f32_e32 v177, v177, v222
	v_add_f32_e32 v177, v177, v223
	v_cvt_pk_bf16_f32 v127, v222, v223
	s_barrier
	global_load_dwordx4 v[128:131], v225, s[8:9]
	s_add_u32 s8, s8, 0x14000
	s_addc_u32 s9, s9, 0
	global_load_dwordx4 v[132:135], v225, s[8:9]
	s_add_u32 s8, s8, 0x14000
	s_addc_u32 s9, s9, 0
	global_load_dwordx4 v[136:139], v225, s[8:9]
	s_add_u32 s8, s8, 0x14000
	s_addc_u32 s9, s9, 0
	global_load_dwordx4 v[140:143], v225, s[8:9]
	s_add_u32 s8, s8, 0x14000
	s_addc_u32 s9, s9, 0
	global_load_dwordx4 v[144:147], v225, s[8:9]
	s_add_u32 s8, s8, 0x14000
	s_addc_u32 s9, s9, 0
	global_load_dwordx4 v[148:151], v225, s[8:9]
	s_add_u32 s8, s8, 0x14000
	s_addc_u32 s9, s9, 0
	global_load_dwordx4 v[152:155], v225, s[8:9]
	s_add_u32 s8, s8, 0x14000
	s_addc_u32 s9, s9, 0
	global_load_dwordx4 v[156:159], v225, s[8:9]
	s_add_u32 s8, s8, 0x14000
	s_addc_u32 s9, s9, 0
	global_load_dwordx4 v[184:187], v225, s[8:9]
	s_add_u32 s8, s8, 0x14000
	s_addc_u32 s9, s9, 0
	global_load_dwordx4 v[188:191], v225, s[8:9]
	s_add_u32 s8, s8, 0x14000
	s_addc_u32 s9, s9, 0
	global_load_dwordx4 v[192:195], v225, s[8:9]
	s_add_u32 s8, s8, 0x14000
	s_addc_u32 s9, s9, 0
	global_load_dwordx4 v[196:199], v225, s[8:9]
	s_add_u32 s8, s8, 0x14000
	s_addc_u32 s9, s9, 0
	global_load_dwordx4 v[200:203], v225, s[8:9]
	s_add_u32 s8, s8, 0x14000
	s_addc_u32 s9, s9, 0
	global_load_dwordx4 v[204:207], v225, s[8:9]
	s_add_u32 s8, s8, 0x14000
	s_addc_u32 s9, s9, 0
	global_load_dwordx4 v[208:211], v225, s[8:9]
	s_add_u32 s8, s8, 0x14000
	s_addc_u32 s9, s9, 0
	global_load_dwordx4 v[212:215], v225, s[8:9]
	s_add_i32 s16, s69, s86
	s_cmpk_lt_i32 s16, 0x300
	s_cselect_b32 s16, s16, s69
	s_and_b32 s0, s16, 31
	s_lshr_b32 s1, s16, 8
	s_lshl_b32 s1, s1, 5
	s_add_i32 s1, s1, s0
	s_mul_i32 s0, s1, 2731
	s_lshr_b32 s0, s0, 16
	s_mul_i32 s17, s0, 24
	s_sub_i32 s1, s1, s17
	s_bfe_u32 s17, s16, 0x30005
	s_mul_i32 s17, s17, 24
	s_add_i32 s1, s1, s17
	s_lshl_b32 s11, s1, 19
	s_lshl_b32 s12, s0, 9
	s_add_u32 s11, s11, s12
	s_add_u32 s12, s11, 0xf000000
	s_add_u32 s10, s4, s12
	s_addc_u32 s11, s5, 0
	s_lshl_b32 s12, s1, 12
	s_lshl_b32 s13, s0, 2
	s_add_u32 s12, s12, s13
	s_add_u32 s12, s12, 0x1fa60000
	s_add_u32 s12, s4, s12
	s_addc_u32 s13, s5, 0
	global_load_dwordx4 v[0:3], v228, s[10:11] offset:0
	global_load_dwordx4 v[4:7], v228, s[10:11] offset:64
	global_load_dwordx4 v[8:11], v228, s[10:11] offset:128
	global_load_dwordx4 v[12:15], v228, s[10:11] offset:192
	global_load_dwordx4 v[16:19], v228, s[10:11] offset:256
	global_load_dwordx4 v[20:23], v228, s[10:11] offset:320
	global_load_dwordx4 v[24:27], v228, s[10:11] offset:384
	global_load_dwordx4 v[28:31], v228, s[10:11] offset:448
	global_load_dwordx4 v[32:35], v229, s[10:11] offset:0
	global_load_dwordx4 v[36:39], v229, s[10:11] offset:64
	global_load_dwordx4 v[40:43], v229, s[10:11] offset:128
	global_load_dwordx4 v[44:47], v229, s[10:11] offset:192
	global_load_dwordx4 v[48:51], v229, s[10:11] offset:256
	global_load_dwordx4 v[52:55], v229, s[10:11] offset:320
	global_load_dwordx4 v[56:59], v229, s[10:11] offset:384
	global_load_dwordx4 v[60:63], v229, s[10:11] offset:448
	global_load_dword v247, v230, s[12:13]
	global_load_dword v248, v230, s[12:13] offset:2048
	ds_bpermute_b32 v242, v236, v176
	s_waitcnt lgkmcnt(0)
	v_add_f32_e32 v176, v176, v242
	ds_bpermute_b32 v242, v237, v176
	s_waitcnt lgkmcnt(0)
	v_add_f32_e32 v176, v176, v242
	ds_bpermute_b32 v242, v236, v177
	s_waitcnt lgkmcnt(0)
	v_add_f32_e32 v177, v177, v242
	ds_bpermute_b32 v242, v237, v177
	s_waitcnt lgkmcnt(0)
	v_add_f32_e32 v177, v177, v242
	v_rcp_f32_e32 v240, v176
	v_rcp_f32_e32 v241, v177
	s_waitcnt vmcnt(30)
	ds_write_b128 v250, v[128:131] offset:0
	ds_write_b128 v250, v[132:135] offset:4224
	ds_write_b128 v250, v[136:139] offset:16896
	ds_write_b128 v250, v[140:143] offset:21120
	s_waitcnt vmcnt(26)
	ds_write_b128 v250, v[144:147] offset:33792
	ds_write_b128 v250, v[148:151] offset:38016
	ds_write_b128 v250, v[152:155] offset:50688
	ds_write_b128 v250, v[156:159] offset:54912
	s_waitcnt vmcnt(22)
	ds_write_b128 v251, v[184:187] offset:0
	ds_write_b128 v251, v[188:191] offset:4224
	ds_write_b128 v251, v[192:195] offset:16896
	ds_write_b128 v251, v[196:199] offset:21120
	s_waitcnt vmcnt(18)
	ds_write_b128 v251, v[200:203] offset:33792
	ds_write_b128 v251, v[204:207] offset:38016
	ds_write_b128 v251, v[208:211] offset:50688
	ds_write_b128 v251, v[212:215] offset:54912
	s_waitcnt lgkmcnt(0)
	s_barrier
	s_and_b32 s0, s16, 31
	s_lshr_b32 s1, s16, 8
	s_lshl_b32 s1, s1, 5
	s_add_i32 s1, s1, s0
	s_mul_i32 s0, s1, 2731
	s_lshr_b32 s0, s0, 16
	s_mul_i32 s17, s0, 24
	s_sub_i32 s1, s1, s17
	s_bfe_u32 s17, s16, 0x30005
	s_mul_i32 s17, s17, 24
	s_add_i32 s1, s1, s17
	s_lshr_b32 s10, s1, 5
	s_sub_i32 s11, s1, 64
	s_lshr_b32 s11, s11, 4
	s_add_i32 s11, s11, 2
	s_cmp_lt_u32 s1, 64
	s_cselect_b32 s10, s10, s11
	s_lshl_b32 s11, s10, 19
	s_lshl_b32 s12, s0, 9
	s_add_u32 s11, s11, s12
	s_add_u32 s11, s11, 0x15040000
	s_add_u32 s6, s4, s11
	s_addc_u32 s7, s5, 0
	global_load_dwordx4 v[184:187], v224, s[6:7]
	s_add_u32 s6, s6, 0x8000
	s_addc_u32 s7, s7, 0
	global_load_dwordx4 v[188:191], v224, s[6:7]
	s_add_u32 s6, s6, 0x8000
	s_addc_u32 s7, s7, 0
	global_load_dwordx4 v[192:195], v224, s[6:7]
	s_add_u32 s6, s6, 0x8000
	s_addc_u32 s7, s7, 0
	global_load_dwordx4 v[196:199], v224, s[6:7]
	s_add_u32 s6, s6, 0x8000
	s_addc_u32 s7, s7, 0
	global_load_dwordx4 v[200:203], v224, s[6:7]
	s_add_u32 s6, s6, 0x8000
	s_addc_u32 s7, s7, 0
	global_load_dwordx4 v[204:207], v224, s[6:7]
	s_add_u32 s6, s6, 0x8000
	s_addc_u32 s7, s7, 0
	global_load_dwordx4 v[208:211], v224, s[6:7]
	s_add_u32 s6, s6, 0x8000
	s_addc_u32 s7, s7, 0
	global_load_dwordx4 v[212:215], v224, s[6:7]
	s_mov_b32 s18, 0
	v_mov_b32_e32 v234, v232
	v_add_u32_e32 v235, 16896, v232
	ds_read_b64 v[128:129], v234 offset:0
	ds_read_b64 v[130:131], v234 offset:32
	ds_read_b64 v[132:133], v234 offset:64
	ds_read_b64 v[134:135], v234 offset:96
	ds_read_b64 v[136:137], v234 offset:128
	ds_read_b64 v[138:139], v234 offset:160
	ds_read_b64 v[140:141], v234 offset:192
	ds_read_b64 v[142:143], v234 offset:224
	ds_read_b64 v[144:145], v234 offset:256
	ds_read_b64 v[146:147], v234 offset:288
	ds_read_b64 v[148:149], v234 offset:320
	ds_read_b64 v[150:151], v234 offset:352
.Lxa_pv:
	ds_read_b64 v[152:153], v234 offset:384
	ds_read_b64 v[154:155], v234 offset:416
	s_waitcnt lgkmcnt(12)
	v_mfma_f32_16x16x32_bf16 v[160:163], v[128:131], v[64:67], 0
	v_mfma_f32_16x16x32_bf16 v[164:167], v[128:131], v[96:99], 0
	ds_read_b64 v[156:157], v234 offset:448
	ds_read_b64 v[158:159], v234 offset:480
	s_waitcnt lgkmcnt(12)
	v_mfma_f32_16x16x32_bf16 v[160:163], v[132:135], v[68:71], v[160:163]
	v_mfma_f32_16x16x32_bf16 v[164:167], v[132:135], v[100:103], v[164:167]
	ds_read_b64 v[128:129], v234 offset:8448
	ds_read_b64 v[130:131], v234 offset:8480
	s_waitcnt lgkmcnt(12)
	v_mfma_f32_16x16x32_bf16 v[160:163], v[136:139], v[72:75], v[160:163]
	v_mfma_f32_16x16x32_bf16 v[164:167], v[136:139], v[104:107], v[164:167]
	ds_read_b64 v[132:133], v234 offset:8512
	ds_read_b64 v[134:135], v234 offset:8544
	s_waitcnt lgkmcnt(12)
	v_mfma_f32_16x16x32_bf16 v[160:163], v[140:143], v[76:79], v[160:163]
	v_mfma_f32_16x16x32_bf16 v[164:167], v[140:143], v[108:111], v[164:167]
	ds_read_b64 v[136:137], v234 offset:8576
	ds_read_b64 v[138:139], v234 offset:8608
	s_waitcnt lgkmcnt(12)
	v_mfma_f32_16x16x32_bf16 v[160:163], v[144:147], v[80:83], v[160:163]
	v_mfma_f32_16x16x32_bf16 v[164:167], v[144:147], v[112:115], v[164:167]
	ds_read_b64 v[140:141], v234 offset:8640
	ds_read_b64 v[142:143], v234 offset:8672
	s_waitcnt lgkmcnt(12)
	v_mfma_f32_16x16x32_bf16 v[160:163], v[148:151], v[84:87], v[160:163]
	v_mfma_f32_16x16x32_bf16 v[164:167], v[148:151], v[116:119], v[164:167]
	ds_read_b64 v[144:145], v234 offset:8704
	ds_read_b64 v[146:147], v234 offset:8736
	s_waitcnt lgkmcnt(12)
	v_mfma_f32_16x16x32_bf16 v[160:163], v[152:155], v[88:91], v[160:163]
	v_mfma_f32_16x16x32_bf16 v[164:167], v[152:155], v[120:123], v[164:167]
	ds_read_b64 v[148:149], v234 offset:8768
	ds_read_b64 v[150:151], v234 offset:8800
	s_waitcnt lgkmcnt(12)
	v_mfma_f32_16x16x32_bf16 v[160:163], v[156:159], v[92:95], v[160:163]
	v_mfma_f32_16x16x32_bf16 v[164:167], v[156:159], v[124:127], v[164:167]
	ds_read_b64 v[152:153], v234 offset:8832
	ds_read_b64 v[154:155], v234 offset:8864
	s_waitcnt lgkmcnt(12)
	v_mfma_f32_16x16x32_bf16 v[168:171], v[128:131], v[64:67], 0
	v_mfma_f32_16x16x32_bf16 v[172:175], v[128:131], v[96:99], 0
	ds_read_b64 v[156:157], v234 offset:8896
	ds_read_b64 v[158:159], v234 offset:8928
	s_waitcnt lgkmcnt(12)
	v_mfma_f32_16x16x32_bf16 v[168:171], v[132:135], v[68:71], v[168:171]
	v_mfma_f32_16x16x32_bf16 v[172:175], v[132:135], v[100:103], v[172:175]
	ds_read_b64 v[128:129], v235 offset:0
	ds_read_b64 v[130:131], v235 offset:32
	s_waitcnt lgkmcnt(12)
	v_mfma_f32_16x16x32_bf16 v[168:171], v[136:139], v[72:75], v[168:171]
	v_mfma_f32_16x16x32_bf16 v[172:175], v[136:139], v[104:107], v[172:175]
	ds_read_b64 v[132:133], v235 offset:64
	ds_read_b64 v[134:135], v235 offset:96
	s_waitcnt lgkmcnt(12)
	v_mfma_f32_16x16x32_bf16 v[168:171], v[140:143], v[76:79], v[168:171]
	v_mfma_f32_16x16x32_bf16 v[172:175], v[140:143], v[108:111], v[172:175]
	ds_read_b64 v[136:137], v235 offset:128
	ds_read_b64 v[138:139], v235 offset:160
	s_waitcnt lgkmcnt(12)
	v_mfma_f32_16x16x32_bf16 v[168:171], v[144:147], v[80:83], v[168:171]
	v_mfma_f32_16x16x32_bf16 v[172:175], v[144:147], v[112:115], v[172:175]
	ds_read_b64 v[140:141], v235 offset:192
	ds_read_b64 v[142:143], v235 offset:224
	s_waitcnt lgkmcnt(12)
	v_mfma_f32_16x16x32_bf16 v[168:171], v[148:151], v[84:87], v[168:171]
	v_mfma_f32_16x16x32_bf16 v[172:175], v[148:151], v[116:119], v[172:175]
	ds_read_b64 v[144:145], v235 offset:256
	ds_read_b64 v[146:147], v235 offset:288
	s_waitcnt lgkmcnt(12)
	v_mfma_f32_16x16x32_bf16 v[168:171], v[152:155], v[88:91], v[168:171]
	v_mfma_f32_16x16x32_bf16 v[172:175], v[152:155], v[120:123], v[172:175]
	ds_read_b64 v[148:149], v235 offset:320
	ds_read_b64 v[150:151], v235 offset:352
	s_waitcnt lgkmcnt(12)
	v_mfma_f32_16x16x32_bf16 v[168:171], v[156:159], v[92:95], v[168:171]
	v_mfma_f32_16x16x32_bf16 v[172:175], v[156:159], v[124:127], v[172:175]
	s_add_i32 s18, s18, 1
	s_add_i32 s19, s18, 1
	s_and_b32 s19, s19, 7
	s_mul_i32 s19, s19, 16896
	s_nop 3
	v_mul_f32_e32 v160, v160, v240
	v_mul_f32_e32 v161, v161, v240
	v_mul_f32_e32 v162, v162, v240
	v_mul_f32_e32 v163, v163, v240
	v_mul_f32_e32 v168, v168, v240
	v_mul_f32_e32 v169, v169, v240
	v_mul_f32_e32 v170, v170, v240
	v_mul_f32_e32 v171, v171, v240
	v_cvt_pk_bf16_f32 v216, v160, v161
	v_cvt_pk_bf16_f32 v217, v162, v163
	v_cvt_pk_bf16_f32 v218, v168, v169
	v_cvt_pk_bf16_f32 v219, v170, v171
	v_mul_f32_e32 v164, v164, v241
	v_mul_f32_e32 v165, v165, v241
	v_mul_f32_e32 v166, v166, v241
	v_mul_f32_e32 v167, v167, v241
	v_mul_f32_e32 v172, v172, v241
	v_mul_f32_e32 v173, v173, v241
	v_mul_f32_e32 v174, v174, v241
	v_mul_f32_e32 v175, v175, v241
	v_cvt_pk_bf16_f32 v220, v164, v165
	v_cvt_pk_bf16_f32 v221, v166, v167
	v_cvt_pk_bf16_f32 v222, v172, v173
	v_cvt_pk_bf16_f32 v223, v174, v175
	global_store_dwordx4 v228, v[216:219], s[14:15]
	global_store_dwordx4 v229, v[220:223], s[14:15]
	s_add_u32 s14, s14, 64
	s_addc_u32 s15, s15, 0
	v_mov_b32_e32 v234, v235
	v_add_u32_e32 v235, s19, v232
	s_cmp_lt_u32 s18, 8
	s_cbranch_scc1 .Lxa_pv
	s_waitcnt lgkmcnt(0)
	s_add_i32 s69, s69, s86
	s_cmpk_lt_i32 s69, 0x300
	s_barrier
	s_cbranch_scc1 .Lxa_unit
	s_setprio 0
